# phase 0 weight transposes: the 8 per-row norm-gain loads issued with the tile row loads instead of 4 serialized load-wait pairs
# speedup vs baseline: 1.0000x; 1.0000x over previous
.LBB0_717:
	s_andn2_b64 vcc, exec, s[4:5]
	s_cbranch_vccnz .LBB0_731
	s_add_i32 s2, s14, 0xfff0
	s_and_b32 s4, s2, 0xff
	v_readlane_b32 s16, v253, 42
	s_mulk_i32 s4, 0xcd
	v_readlane_b32 s17, v253, 43
	s_bfe_u32 s12, s4, 0x3000d
	s_load_dwordx4 s[4:7], s[16:17], 0x58
	s_mul_i32 s11, s12, 40
	s_sub_i32 s2, s2, s11
	s_and_b32 s11, s2, 0xff
	s_mul_i32 s13, s10, 0xa08000
	s_mul_hi_i32 s2, s10, 0xa08000
	s_waitcnt lgkmcnt(0)
	s_add_u32 s13, s6, s13
	s_addc_u32 s16, s7, s2
	s_lshl_b32 s6, s10, 10
	s_ashr_i32 s7, s6, 31
	s_lshl_b32 s2, s12, 8
	s_lshl_b64 s[6:7], s[6:7], 2
	s_add_u32 s6, s4, s6
	s_addc_u32 s7, s5, s7
	v_mov_b32_e32 v50, v201
	s_lshl_b32 s12, s11, 8
	s_add_u32 s12, s13, s12
	v_lshlrev_b32_e32 v0, 4, v50
	v_add_u32_e32 v53, 0x200, v50
	s_addc_u32 s13, s16, 0
	v_and_b32_e32 v0, 0xf0, v0
	v_ashrrev_i32_e32 v45, 4, v50
	v_ashrrev_i32_e32 v43, 4, v53
	v_add_u32_e32 v52, 0x400, v50
	v_add_u32_e32 v51, 0x600, v50
	v_lshl_add_u64 v[2:3], s[12:13], 0, v[0:1]
	v_add_u32_e32 v46, s2, v45
	s_movk_i32 s16, 0x2820
	v_add_u32_e32 v48, s2, v43
	v_ashrrev_i32_e32 v41, 4, v52
	v_ashrrev_i32_e32 v39, 4, v51
	v_mad_i64_i32 v[4:5], s[12:13], v46, s16, v[2:3]
	v_mad_i64_i32 v[6:7], s[12:13], v48, s16, v[2:3]
	v_add_u32_e32 v44, s2, v41
	v_add_u32_e32 v42, s2, v39
	s_barrier
	global_load_dwordx4 v[30:33], v[4:5], off
	global_load_dwordx4 v[26:29], v[6:7], off
	v_mad_i64_i32 v[4:5], s[12:13], v44, s16, v[2:3]
	v_mad_i64_i32 v[6:7], s[12:13], v42, s16, v[2:3]
	global_load_dwordx4 v[22:25], v[4:5], off
	global_load_dwordx4 v[18:21], v[6:7], off
	v_add_u32_e32 v4, 0x800, v50
	v_add_u32_e32 v6, 0xa00, v50
	v_ashrrev_i32_e32 v37, 4, v4
	v_ashrrev_i32_e32 v35, 4, v6
	v_add_u32_e32 v40, s2, v37
	v_add_u32_e32 v38, s2, v35
	v_mad_i64_i32 v[4:5], s[12:13], v40, s16, v[2:3]
	v_mad_i64_i32 v[6:7], s[12:13], v38, s16, v[2:3]
	global_load_dwordx4 v[14:17], v[4:5], off
	global_load_dwordx4 v[10:13], v[6:7], off
	v_add_u32_e32 v4, 0xc00, v50
	v_add_u32_e32 v6, 0xe00, v50
	v_ashrrev_i32_e32 v55, 4, v4
	v_ashrrev_i32_e32 v54, 4, v6
	v_add_u32_e32 v36, s2, v55
	v_add_u32_e32 v34, s2, v54
	v_mad_i64_i32 v[4:5], s[12:13], v36, s16, v[2:3]
	v_mad_i64_i32 v[2:3], s[12:13], v34, s16, v[2:3]
	global_load_dwordx4 v[6:9], v[4:5], off
	s_nop 0
	global_load_dwordx4 v[2:5], v[2:3], off
	s_cmp_eq_u64 s[4:5], 0
	s_cbranch_scc1 .Lwgk_skip_0
	v_mov_b32_e32 v68, v46
	v_ashrrev_i32_e32 v69, 31, v46
	v_lshl_add_u64 v[68:69], v[68:69], 2, s[6:7]
	global_load_dword v60, v[68:69], off
	v_mov_b32_e32 v68, v48
	v_ashrrev_i32_e32 v69, 31, v48
	v_lshl_add_u64 v[68:69], v[68:69], 2, s[6:7]
	global_load_dword v61, v[68:69], off
	v_mov_b32_e32 v68, v44
	v_ashrrev_i32_e32 v69, 31, v44
	v_lshl_add_u64 v[68:69], v[68:69], 2, s[6:7]
	global_load_dword v62, v[68:69], off
	v_mov_b32_e32 v68, v42
	v_ashrrev_i32_e32 v69, 31, v42
	v_lshl_add_u64 v[68:69], v[68:69], 2, s[6:7]
	global_load_dword v63, v[68:69], off
	v_mov_b32_e32 v68, v40
	v_ashrrev_i32_e32 v69, 31, v40
	v_lshl_add_u64 v[68:69], v[68:69], 2, s[6:7]
	global_load_dword v64, v[68:69], off
	v_mov_b32_e32 v68, v38
	v_ashrrev_i32_e32 v69, 31, v38
	v_lshl_add_u64 v[68:69], v[68:69], 2, s[6:7]
	global_load_dword v65, v[68:69], off
	v_mov_b32_e32 v68, v36
	v_ashrrev_i32_e32 v69, 31, v36
	v_lshl_add_u64 v[68:69], v[68:69], 2, s[6:7]
	global_load_dword v66, v[68:69], off
	v_mov_b32_e32 v68, v34
	v_ashrrev_i32_e32 v69, 31, v34
	v_lshl_add_u64 v[68:69], v[68:69], 2, s[6:7]
	global_load_dword v67, v[68:69], off
.Lwgk_skip_0:
	s_cmp_lg_u64 s[4:5], 0
	s_cselect_b64 s[12:13], -1, 0
	s_cmp_eq_u64 s[4:5], 0
	v_add_u32_e32 v0, 0, v0
	s_cbranch_scc1 .LBB0_747
	v_ashrrev_i32_e32 v47, 31, v46
	v_lshl_add_u64 v[46:47], v[46:47], 2, s[6:7]
	v_ashrrev_i32_e32 v49, 31, v48
	s_waitcnt vmcnt(6)
	v_mov_b32_e32 v56, v60
	v_lshl_add_u64 v[46:47], v[48:49], 2, s[6:7]
	v_mov_b32_e32 v46, v61
	s_movk_i32 s4, 0x104
	v_mad_u64_u32 v[48:49], s[4:5], v45, s4, v[0:1]
	s_waitcnt vmcnt(1)
	v_pk_mul_f32 v[58:59], v[30:31], v[56:57] op_sel_hi:[1,0]
	v_pk_mul_f32 v[56:57], v[32:33], v[56:57] op_sel_hi:[1,0]
	ds_write2_b32 v48, v58, v59 offset1:1
	ds_write2_b32 v48, v56, v57 offset0:2 offset1:3
	s_cbranch_execnz .LBB0_721

.LBB0_721:
	s_movk_i32 s16, 0x104
	s_waitcnt vmcnt(7)
	v_mad_u64_u32 v[30:31], s[4:5], v43, s16, v[0:1]
	s_waitcnt vmcnt(0)
	v_pk_mul_f32 v[26:27], v[26:27], v[46:47] op_sel_hi:[1,0]
	ds_write2_b32 v30, v26, v27 offset1:1
	v_pk_mul_f32 v[26:27], v[28:29], v[46:47] op_sel_hi:[1,0]
	v_cndmask_b32_e64 v28, 0, 1, s[12:13]
	v_cmp_ne_u32_e64 s[4:5], 1, v28
	s_andn2_b64 vcc, exec, s[12:13]
	ds_write2_b32 v30, v26, v27 offset0:2 offset1:3
	s_cbranch_vccnz .LBB0_748
	v_ashrrev_i32_e32 v45, 31, v44
	v_lshl_add_u64 v[26:27], v[44:45], 2, s[6:7]
	v_ashrrev_i32_e32 v43, 31, v42
	s_waitcnt vmcnt(4)
	v_mov_b32_e32 v28, v62
	v_lshl_add_u64 v[26:27], v[42:43], 2, s[6:7]
	v_mov_b32_e32 v26, v63
	v_mad_u64_u32 v[30:31], s[12:13], v41, s16, v[0:1]
	s_movk_i32 s17, 0x104
	s_waitcnt vmcnt(1)
	v_pk_mul_f32 v[32:33], v[22:23], v[28:29] op_sel_hi:[1,0]
	v_pk_mul_f32 v[28:29], v[24:25], v[28:29] op_sel_hi:[1,0]
	ds_write2_b32 v30, v32, v33 offset1:1
	ds_write2_b32 v30, v28, v29 offset0:2 offset1:3
	s_cbranch_execnz .LBB0_724

.LBB0_724:
	v_mad_u64_u32 v[22:23], s[12:13], v39, s16, v[0:1]
	s_waitcnt vmcnt(0)
	v_pk_mul_f32 v[18:19], v[18:19], v[26:27] op_sel_hi:[1,0]
	ds_write2_b32 v22, v18, v19 offset1:1
	v_pk_mul_f32 v[18:19], v[20:21], v[26:27] op_sel_hi:[1,0]
	s_and_b64 vcc, exec, s[4:5]
	ds_write2_b32 v22, v18, v19 offset0:2 offset1:3
	s_cbranch_vccnz .LBB0_749
	v_ashrrev_i32_e32 v41, 31, v40
	v_lshl_add_u64 v[18:19], v[40:41], 2, s[6:7]
	v_ashrrev_i32_e32 v39, 31, v38
	s_waitcnt vmcnt(2)
	v_mov_b32_e32 v20, v64
	v_lshl_add_u64 v[18:19], v[38:39], 2, s[6:7]
	v_mov_b32_e32 v18, v65
	v_mad_u64_u32 v[22:23], s[12:13], v37, s16, v[0:1]
	s_waitcnt vmcnt(1)
	v_pk_mul_f32 v[24:25], v[14:15], v[20:21] op_sel_hi:[1,0]
	v_pk_mul_f32 v[20:21], v[16:17], v[20:21] op_sel_hi:[1,0]
	ds_write2_b32 v22, v24, v25 offset1:1
	ds_write2_b32 v22, v20, v21 offset0:2 offset1:3
	s_cbranch_execnz .LBB0_727

.LBB0_727:
	v_mad_u64_u32 v[14:15], s[12:13], v35, s16, v[0:1]
	s_waitcnt vmcnt(0)
	v_pk_mul_f32 v[10:11], v[10:11], v[18:19] op_sel_hi:[1,0]
	ds_write2_b32 v14, v10, v11 offset1:1
	v_pk_mul_f32 v[10:11], v[12:13], v[18:19] op_sel_hi:[1,0]
	s_and_b64 vcc, exec, s[4:5]
	ds_write2_b32 v14, v10, v11 offset0:2 offset1:3
	s_cbranch_vccnz .LBB0_750
	v_ashrrev_i32_e32 v37, 31, v36
	v_lshl_add_u64 v[10:11], v[36:37], 2, s[6:7]
	v_ashrrev_i32_e32 v35, 31, v34
	s_waitcnt vmcnt(0)
	v_mov_b32_e32 v12, v66
	v_lshl_add_u64 v[10:11], v[34:35], 2, s[6:7]
	v_mov_b32_e32 v10, v67
	v_mad_u64_u32 v[14:15], s[4:5], v55, s16, v[0:1]
	s_waitcnt vmcnt(1)
	v_pk_mul_f32 v[16:17], v[6:7], v[12:13] op_sel_hi:[1,0]
	v_pk_mul_f32 v[12:13], v[8:9], v[12:13] op_sel_hi:[1,0]
	ds_write2_b32 v14, v16, v17 offset1:1
	ds_write2_b32 v14, v12, v13 offset0:2 offset1:3
	s_cbranch_execnz .LBB0_730

.LBB0_735:
	s_andn2_b64 vcc, exec, s[4:5]
	s_cbranch_vccnz .LBB0_713
	s_and_b64 s[4:5], s[6:7], exec
	s_movk_i32 s2, 0x48
	s_cselect_b32 s2, 0xc0, s2
	v_readlane_b32 s26, v253, 42
	v_readlane_b32 s27, v253, 43
	s_add_u32 s4, s26, s2
	s_addc_u32 s5, s27, 0
	s_and_b64 s[14:15], s[6:7], exec
	s_cselect_b32 s2, 0xb8, 64
	s_add_u32 s14, s26, s2
	s_addc_u32 s15, s27, 0
	s_add_i32 s2, s13, 0xff50
	s_cmpk_gt_i32 s13, 0xaf
	s_load_dwordx2 s[4:5], s[4:5], 0x0
	s_nop 0
	s_load_dwordx2 s[16:17], s[14:15], 0x0
	s_cselect_b64 s[14:15], -1, 0
	s_and_b64 s[18:19], s[14:15], exec
	s_cselect_b32 s2, s2, s13
	s_sext_i32_i16 s13, s2
	s_mulk_i32 s13, 0xba3
	s_waitcnt lgkmcnt(0)
	s_cselect_b32 s5, s5, s17
	s_cselect_b32 s4, s4, s16
	s_lshr_b32 s16, s13, 31
	s_ashr_i32 s13, s13, 17
	s_add_i32 s13, s13, s16
	s_mul_i32 s16, s13, 44
	s_sub_i32 s2, s2, s16
	s_sext_i32_i16 s2, s2
	s_lshl_b32 s16, s2, 6
	s_add_u32 s24, s4, s12
	s_addc_u32 s25, s5, s11
	s_lshl_b32 s12, s13, 8
	s_and_b64 s[4:5], s[6:7], exec
	s_cselect_b32 s4, 0xb0, 56
	s_add_u32 s4, s26, s4
	s_addc_u32 s5, s27, 0
	s_load_dwordx2 s[4:5], s[4:5], 0x0
	s_lshl_b32 s10, s10, 10
	s_ashr_i32 s11, s10, 31
	s_lshl_b64 s[10:11], s[10:11], 2
	v_mov_b32_e32 v50, v201
	s_waitcnt lgkmcnt(0)
	s_add_u32 s10, s4, s10
	s_addc_u32 s11, s5, s11
	s_ashr_i32 s17, s16, 31
	s_lshl_b64 s[18:19], s[16:17], 2
	s_add_u32 s18, s24, s18
	v_lshlrev_b32_e32 v0, 4, v50
	v_add_u32_e32 v53, 0x200, v50
	s_addc_u32 s19, s25, s19
	v_and_b32_e32 v0, 0xf0, v0
	v_ashrrev_i32_e32 v45, 4, v50
	v_ashrrev_i32_e32 v43, 4, v53
	v_add_u32_e32 v52, 0x400, v50
	v_add_u32_e32 v51, 0x600, v50
	v_lshl_add_u64 v[2:3], s[18:19], 0, v[0:1]
	v_add_u32_e32 v46, s12, v45
	s_movk_i32 s13, 0x2c00
	v_add_u32_e32 v48, s12, v43
	v_ashrrev_i32_e32 v41, 4, v52
	v_ashrrev_i32_e32 v39, 4, v51
	v_mad_i64_i32 v[4:5], s[18:19], v46, s13, v[2:3]
	v_mad_i64_i32 v[6:7], s[18:19], v48, s13, v[2:3]
	v_add_u32_e32 v44, s12, v41
	v_add_u32_e32 v42, s12, v39
	s_barrier
	global_load_dwordx4 v[30:33], v[4:5], off
	global_load_dwordx4 v[26:29], v[6:7], off
	v_mad_i64_i32 v[4:5], s[18:19], v44, s13, v[2:3]
	v_mad_i64_i32 v[6:7], s[18:19], v42, s13, v[2:3]
	global_load_dwordx4 v[22:25], v[4:5], off
	global_load_dwordx4 v[18:21], v[6:7], off
	v_add_u32_e32 v4, 0x800, v50
	v_add_u32_e32 v6, 0xa00, v50
	v_ashrrev_i32_e32 v37, 4, v4
	v_ashrrev_i32_e32 v35, 4, v6
	v_add_u32_e32 v40, s12, v37
	v_add_u32_e32 v38, s12, v35
	v_mad_i64_i32 v[4:5], s[18:19], v40, s13, v[2:3]
	v_mad_i64_i32 v[6:7], s[18:19], v38, s13, v[2:3]
	global_load_dwordx4 v[14:17], v[4:5], off
	global_load_dwordx4 v[10:13], v[6:7], off
	v_add_u32_e32 v4, 0xc00, v50
	v_add_u32_e32 v6, 0xe00, v50
	v_ashrrev_i32_e32 v55, 4, v4
	v_ashrrev_i32_e32 v54, 4, v6
	v_add_u32_e32 v36, s12, v55
	v_add_u32_e32 v34, s12, v54
	v_mad_i64_i32 v[4:5], s[18:19], v36, s13, v[2:3]
	v_mad_i64_i32 v[2:3], s[18:19], v34, s13, v[2:3]
	global_load_dwordx4 v[6:9], v[4:5], off
	s_nop 0
	global_load_dwordx4 v[2:5], v[2:3], off
	s_cmp_eq_u64 s[4:5], 0
	s_cbranch_scc1 .Lwgk_skip_1
	v_mov_b32_e32 v68, v46
	v_ashrrev_i32_e32 v69, 31, v46
	v_lshl_add_u64 v[68:69], v[68:69], 2, s[10:11]
	global_load_dword v60, v[68:69], off
	v_mov_b32_e32 v68, v48
	v_ashrrev_i32_e32 v69, 31, v48
	v_lshl_add_u64 v[68:69], v[68:69], 2, s[10:11]
	global_load_dword v61, v[68:69], off
	v_mov_b32_e32 v68, v44
	v_ashrrev_i32_e32 v69, 31, v44
	v_lshl_add_u64 v[68:69], v[68:69], 2, s[10:11]
	global_load_dword v62, v[68:69], off
	v_mov_b32_e32 v68, v42
	v_ashrrev_i32_e32 v69, 31, v42
	v_lshl_add_u64 v[68:69], v[68:69], 2, s[10:11]
	global_load_dword v63, v[68:69], off
	v_mov_b32_e32 v68, v40
	v_ashrrev_i32_e32 v69, 31, v40
	v_lshl_add_u64 v[68:69], v[68:69], 2, s[10:11]
	global_load_dword v64, v[68:69], off
	v_mov_b32_e32 v68, v38
	v_ashrrev_i32_e32 v69, 31, v38
	v_lshl_add_u64 v[68:69], v[68:69], 2, s[10:11]
	global_load_dword v65, v[68:69], off
	v_mov_b32_e32 v68, v36
	v_ashrrev_i32_e32 v69, 31, v36
	v_lshl_add_u64 v[68:69], v[68:69], 2, s[10:11]
	global_load_dword v66, v[68:69], off
	v_mov_b32_e32 v68, v34
	v_ashrrev_i32_e32 v69, 31, v34
	v_lshl_add_u64 v[68:69], v[68:69], 2, s[10:11]
	global_load_dword v67, v[68:69], off
.Lwgk_skip_1:
	s_cmp_lg_u64 s[4:5], 0
	s_cselect_b64 s[18:19], -1, 0
	s_cmp_eq_u64 s[4:5], 0
	v_add_u32_e32 v0, 0, v0
	s_cbranch_scc1 .LBB0_751
	v_ashrrev_i32_e32 v47, 31, v46
	v_lshl_add_u64 v[46:47], v[46:47], 2, s[10:11]
	v_ashrrev_i32_e32 v49, 31, v48
	s_waitcnt vmcnt(6)
	v_mov_b32_e32 v56, v60
	v_lshl_add_u64 v[46:47], v[48:49], 2, s[10:11]
	v_mov_b32_e32 v46, v61
	s_movk_i32 s4, 0x104
	v_mad_u64_u32 v[48:49], s[4:5], v45, s4, v[0:1]
	s_waitcnt vmcnt(1)
	v_pk_mul_f32 v[58:59], v[30:31], v[56:57] op_sel_hi:[1,0]
	v_pk_mul_f32 v[56:57], v[32:33], v[56:57] op_sel_hi:[1,0]
	ds_write2_b32 v48, v58, v59 offset1:1
	ds_write2_b32 v48, v56, v57 offset0:2 offset1:3
	s_cbranch_execnz .LBB0_739

.LBB0_739:
	s_movk_i32 s13, 0x104
	s_waitcnt vmcnt(7)
	v_mad_u64_u32 v[30:31], s[4:5], v43, s13, v[0:1]
	s_waitcnt vmcnt(0)
	v_pk_mul_f32 v[26:27], v[26:27], v[46:47] op_sel_hi:[1,0]
	ds_write2_b32 v30, v26, v27 offset1:1
	v_pk_mul_f32 v[26:27], v[28:29], v[46:47] op_sel_hi:[1,0]
	v_cndmask_b32_e64 v28, 0, 1, s[18:19]
	v_cmp_ne_u32_e64 s[4:5], 1, v28
	s_andn2_b64 vcc, exec, s[18:19]
	ds_write2_b32 v30, v26, v27 offset0:2 offset1:3
	s_cbranch_vccnz .LBB0_752
	v_ashrrev_i32_e32 v45, 31, v44
	v_lshl_add_u64 v[26:27], v[44:45], 2, s[10:11]
	v_ashrrev_i32_e32 v43, 31, v42
	s_waitcnt vmcnt(4)
	v_mov_b32_e32 v28, v62
	v_lshl_add_u64 v[26:27], v[42:43], 2, s[10:11]
	v_mov_b32_e32 v26, v63
	v_mad_u64_u32 v[30:31], s[18:19], v41, s13, v[0:1]
	s_movk_i32 s17, 0x104
	s_waitcnt vmcnt(1)
	v_pk_mul_f32 v[32:33], v[22:23], v[28:29] op_sel_hi:[1,0]
	v_pk_mul_f32 v[28:29], v[24:25], v[28:29] op_sel_hi:[1,0]
	ds_write2_b32 v30, v32, v33 offset1:1
	ds_write2_b32 v30, v28, v29 offset0:2 offset1:3
	s_cbranch_execnz .LBB0_742

.LBB0_742:
	v_mad_u64_u32 v[22:23], s[18:19], v39, s13, v[0:1]
	s_waitcnt vmcnt(0)
	v_pk_mul_f32 v[18:19], v[18:19], v[26:27] op_sel_hi:[1,0]
	ds_write2_b32 v22, v18, v19 offset1:1
	v_pk_mul_f32 v[18:19], v[20:21], v[26:27] op_sel_hi:[1,0]
	s_and_b64 vcc, exec, s[4:5]
	ds_write2_b32 v22, v18, v19 offset0:2 offset1:3
	s_cbranch_vccnz .LBB0_753
	v_ashrrev_i32_e32 v41, 31, v40
	v_lshl_add_u64 v[18:19], v[40:41], 2, s[10:11]
	v_ashrrev_i32_e32 v39, 31, v38
	s_waitcnt vmcnt(2)
	v_mov_b32_e32 v20, v64
	v_lshl_add_u64 v[18:19], v[38:39], 2, s[10:11]
	v_mov_b32_e32 v18, v65
	v_mad_u64_u32 v[22:23], s[18:19], v37, s13, v[0:1]
	s_waitcnt vmcnt(1)
	v_pk_mul_f32 v[24:25], v[14:15], v[20:21] op_sel_hi:[1,0]
	v_pk_mul_f32 v[20:21], v[16:17], v[20:21] op_sel_hi:[1,0]
	ds_write2_b32 v22, v24, v25 offset1:1
	ds_write2_b32 v22, v20, v21 offset0:2 offset1:3
	s_cbranch_execnz .LBB0_745

.LBB0_745:
	v_mad_u64_u32 v[14:15], s[18:19], v35, s13, v[0:1]
	s_waitcnt vmcnt(0)
	v_pk_mul_f32 v[10:11], v[10:11], v[18:19] op_sel_hi:[1,0]
	ds_write2_b32 v14, v10, v11 offset1:1
	v_pk_mul_f32 v[10:11], v[12:13], v[18:19] op_sel_hi:[1,0]
	s_and_b64 vcc, exec, s[4:5]
	ds_write2_b32 v14, v10, v11 offset0:2 offset1:3
	s_cbranch_vccnz .LBB0_754
	v_ashrrev_i32_e32 v37, 31, v36
	v_lshl_add_u64 v[10:11], v[36:37], 2, s[10:11]
	v_ashrrev_i32_e32 v35, 31, v34
	s_waitcnt vmcnt(0)
	v_mov_b32_e32 v12, v66
	v_lshl_add_u64 v[10:11], v[34:35], 2, s[10:11]
	v_mov_b32_e32 v10, v67
	v_mad_u64_u32 v[14:15], s[4:5], v55, s13, v[0:1]
	s_waitcnt vmcnt(1)
	v_pk_mul_f32 v[16:17], v[6:7], v[12:13] op_sel_hi:[1,0]
	v_pk_mul_f32 v[12:13], v[8:9], v[12:13] op_sel_hi:[1,0]
	ds_write2_b32 v14, v16, v17 offset1:1
	ds_write2_b32 v14, v12, v13 offset0:2 offset1:3
	s_cbranch_execnz .LBB0_712
	s_branch .LBB0_755

.LBB0_754:
.LBB0_755:
	s_movk_i32 s4, 0x104
	s_waitcnt vmcnt(0)
	v_mad_u64_u32 v[10:11], s[4:5], v55, s4, v[0:1]
	ds_write2_b32 v10, v6, v7 offset1:1
	ds_write2_b32 v10, v8, v9 offset0:2 offset1:3
	v_mov_b32_e32 v10, 1.0
	s_branch .LBB0_712
	s_nop 0
	s_nop 0
	s_nop 0
	s_nop 0
